# prep2 Lw/La loads issued with the row loads; weight transpose loads batched 32 deep; prep1 next-row L2 prefetch
# speedup vs baseline: 1.0201x; 1.0048x over previous
; __device__ __forceinline__ float sigmoid_f(float x) { return __builtin_amdgcn_rcpf(1.0f + __expf(-x)); }
; __device__ __forceinline__ void prep2_phase(const Args& a, int e) {
;     ...
;         float lw[8], la[8], u[8], av[8], kk[8], km[8], ka[8];
;         unpack8(*(const v4u*)(Lw + (size_t)m * 512 + c8), lw); unpack8(*(const v4u*)(La + (size_t)m * 512 + c8), la);
;         float ss = 0.f;
; #pragma unroll
;         for (int i = 0; i < 8; ++i) {
;             u[i] = 1.0f - __expf(-0.6065306597126334f * sigmoid_f(w0[i] + lw[i]));
;             av[i] = sigmoid_f(a0[i] + la[i]);
;             kk[i] = k[i] * kkw[i]; ss += kk[i] * kk[i];
;             km[i] = k[i] * (1.0f + (av[i] - 1.0f) * kaw[i]);
;         }
.LBB0_265:
	s_or_b64 exec, exec, s[0:1]
	v_lshl_add_u64 v[130:131], s[22:23], 0, v[96:97]
	s_mov_b32 s0, 0xe780000
	v_add_co_u32_e32 v126, vcc, s0, v130
	s_mov_b32 s0, 0x12880000
	s_nop 0
	v_addc_co_u32_e32 v127, vcc, 0, v131, vcc
	s_waitcnt vmcnt(0)
	v_mov_b32_e32 v126, v64
	v_mov_b32_e32 v127, v65
	v_mov_b32_e32 v128, v66
	v_mov_b32_e32 v129, v67
	v_add_u32_e32 v62, s64, v62
	v_lshl_add_u64 v[96:97], v[96:97], 0, s[36:37]
	s_waitcnt vmcnt(0)
	v_lshlrev_b32_e32 v63, 16, v126
	v_and_b32_e32 v133, 0xffff0000, v126
	v_add_co_u32_e32 v126, vcc, s0, v130
	v_lshlrev_b32_e32 v141, 16, v127
	v_and_b32_e32 v143, 0xffff0000, v127
	v_addc_co_u32_e32 v127, vcc, 0, v131, vcc
	v_lshlrev_b32_e32 v149, 16, v128
	v_and_b32_e32 v145, 0xffff0000, v128
	v_lshlrev_b32_e32 v138, 16, v129
	v_and_b32_e32 v136, 0xffff0000, v129
	s_waitcnt vmcnt(0)
	v_mov_b32_e32 v126, v68
	v_mov_b32_e32 v127, v69
	v_mov_b32_e32 v128, v70
	v_mov_b32_e32 v129, v71
	v_add_f32_e32 v63, v26, v63
	v_mul_f32_e32 v63, 0xbfb8aa3b, v63
	v_exp_f32_e32 v63, v63
	v_add_f32_e32 v145, v31, v145
	v_mul_f32_e32 v145, 0xbfb8aa3b, v145
	v_exp_f32_e32 v145, v145
	v_add_f32_e32 v63, 1.0, v63
	v_rcp_f32_e32 v63, v63
	s_mov_b32 s0, 0x1aa80000
	v_add_f32_e32 v145, 1.0, v145
	v_rcp_f32_e32 v145, v145
	v_mul_f32_e32 v63, 0xbf1b4598, v63
	v_mul_f32_e32 v63, 0x3fb8aa3b, v63
	v_exp_f32_e32 v63, v63
	v_mul_f32_e32 v145, 0xbf1b4598, v145
	v_mul_f32_e32 v145, 0x3fb8aa3b, v145
	v_exp_f32_e32 v145, v145
	v_sub_f32_e32 v132, 1.0, v63
	v_sub_f32_e32 v145, 1.0, v145
	s_waitcnt vmcnt(0)
	v_lshlrev_b32_e32 v131, 16, v127
	v_and_b32_e32 v147, 0xffff0000, v127
	v_add_f32_e32 v127, v27, v133
	v_mul_f32_e32 v127, 0xbfb8aa3b, v127
	v_exp_f32_e32 v127, v127
	v_lshlrev_b32_e32 v130, 16, v126
	v_add_f32_e32 v63, v34, v130
	v_and_b32_e32 v126, 0xffff0000, v126
	v_mul_f32_e32 v63, 0xbfb8aa3b, v63
	v_exp_f32_e32 v63, v63
	v_add_f32_e32 v127, 1.0, v127
	v_add_f32_e32 v126, v35, v126
	v_rcp_f32_e32 v127, v127
	v_mul_f32_e32 v126, 0xbfb8aa3b, v126
	v_exp_f32_e32 v126, v126
	v_add_f32_e32 v63, 1.0, v63
	v_rcp_f32_e32 v134, v63
	v_mul_f32_e32 v127, 0xbf1b4598, v127
	v_mul_f32_e32 v127, 0x3fb8aa3b, v127
	v_add_f32_e32 v126, 1.0, v126
	v_exp_f32_e32 v127, v127
	v_rcp_f32_e32 v135, v126
	v_add_f32_e32 v63, -1.0, v134
	v_fma_f32 v63, v42, v63, 1.0
	v_mul_f32_e32 v63, v124, v63
	v_sub_f32_e32 v133, 1.0, v127
	v_pk_mul_f32 v[126:127], v[54:55], v[124:125]
	v_add_f32_e32 v124, -1.0, v135
	v_fma_f32 v124, v43, v124, 1.0
	v_mul_f32_e32 v140, v125, v124
	v_add_f32_e32 v124, v28, v141
	v_mul_f32_e32 v124, 0xbfb8aa3b, v124
	v_exp_f32_e32 v124, v124
	v_lshlrev_b32_e32 v148, 16, v128
	v_add_f32_e32 v148, v38, v148
	v_and_b32_e32 v146, 0xffff0000, v128
	v_add_f32_e32 v124, 1.0, v124
	v_rcp_f32_e32 v124, v124
	v_mul_f32_e32 v148, 0xbfb8aa3b, v148
	v_exp_f32_e32 v148, v148
	v_add_f32_e32 v146, v39, v146
	v_mul_f32_e32 v124, 0xbf1b4598, v124
	v_mul_f32_e32 v124, 0x3fb8aa3b, v124
	v_exp_f32_e32 v124, v124
	v_mul_f32_e32 v146, 0xbfb8aa3b, v146
	v_exp_f32_e32 v146, v146
	v_add_f32_e32 v148, 1.0, v148
	v_sub_f32_e32 v142, 1.0, v124
	v_add_f32_e32 v124, v36, v131
	v_mul_f32_e32 v124, 0xbfb8aa3b, v124
	v_exp_f32_e32 v124, v124
	v_rcp_f32_e32 v158, v148
	v_add_f32_e32 v146, 1.0, v146
	v_rcp_f32_e32 v146, v146
	v_add_f32_e32 v124, 1.0, v124
	v_rcp_f32_e32 v144, v124
	v_add_f32_e32 v148, -1.0, v158
	v_fma_f32 v148, v46, v148, 1.0
	v_mul_f32_e32 v160, v118, v148
	v_add_f32_e32 v124, -1.0, v144
	v_fma_f32 v124, v44, v124, 1.0
	v_mul_f32_e32 v141, v122, v124
	v_add_f32_e32 v124, v29, v143
	v_mul_f32_e32 v124, 0xbfb8aa3b, v124
	v_exp_f32_e32 v124, v124
	v_lshlrev_b32_e32 v139, 16, v129
	v_and_b32_e32 v137, 0xffff0000, v129
	v_pk_mul_f32 v[128:129], v[126:127], v[126:127]
	v_add_f32_e32 v124, 1.0, v124
	v_rcp_f32_e32 v124, v124
	s_nop 0
	v_mul_f32_e32 v124, 0xbf1b4598, v124
	v_mul_f32_e32 v124, 0x3fb8aa3b, v124
	v_exp_f32_e32 v124, v124
	s_nop 0
	v_sub_f32_e32 v143, 1.0, v124
	v_add_f32_e32 v124, v37, v147
	v_mul_f32_e32 v124, 0xbfb8aa3b, v124
	v_exp_f32_e32 v124, v124
	s_nop 0
	v_add_f32_e32 v124, 1.0, v124
	v_rcp_f32_e32 v147, v124
	v_pk_mul_f32 v[124:125], v[56:57], v[122:123]
	v_add_f32_e32 v122, -1.0, v147
	v_fma_f32 v122, v45, v122, 1.0
	v_mul_f32_e32 v122, v123, v122
	v_add_f32_e32 v123, v30, v149
	v_pk_mul_f32 v[148:149], v[58:59], v[118:119]
	v_add_f32_e32 v118, -1.0, v146
	v_fma_f32 v118, v47, v118, 1.0
	v_mul_f32_e32 v161, v119, v118
	v_add_f32_e32 v118, v32, v138
	v_mul_f32_e32 v118, 0xbfb8aa3b, v118
	v_exp_f32_e32 v118, v118
	v_pk_mul_f32 v[130:131], v[124:125], v[124:125]
	v_pk_mul_f32 v[156:157], v[148:149], v[148:149]
	v_mul_f32_e32 v123, 0xbfb8aa3b, v123
	v_add_f32_e32 v118, 1.0, v118
	v_rcp_f32_e32 v118, v118
	v_exp_f32_e32 v123, v123
	v_mul_f32_e32 v118, 0xbf1b4598, v118
	v_mul_f32_e32 v118, 0x3fb8aa3b, v118
	v_exp_f32_e32 v118, v118
	v_add_f32_e32 v123, 1.0, v123
	v_rcp_f32_e32 v123, v123
	v_sub_f32_e32 v138, 1.0, v118
	v_add_f32_e32 v118, v40, v139
	v_mul_f32_e32 v118, 0xbfb8aa3b, v118
	v_exp_f32_e32 v118, v118
	v_mul_f32_e32 v123, 0xbf1b4598, v123
	v_mul_f32_e32 v123, 0x3fb8aa3b, v123
	v_exp_f32_e32 v123, v123
	v_add_f32_e32 v118, 1.0, v118
	v_rcp_f32_e32 v139, v118
	v_sub_f32_e32 v123, 1.0, v123
	v_add_f32_e32 v118, -1.0, v139
	v_fma_f32 v118, v48, v118, 1.0
	v_mul_f32_e32 v162, v102, v118
	v_add_f32_e32 v118, v33, v136
	v_mul_f32_e32 v118, 0xbfb8aa3b, v118
	v_exp_f32_e32 v118, v118
	s_nop 0
	v_add_f32_e32 v118, 1.0, v118
	v_rcp_f32_e32 v118, v118
	s_nop 0
	v_mul_f32_e32 v118, 0xbf1b4598, v118
	v_mul_f32_e32 v118, 0x3fb8aa3b, v118
	v_exp_f32_e32 v118, v118
	s_nop 0
	v_sub_f32_e32 v163, 1.0, v118
	v_add_f32_e32 v118, v41, v137
; __device__ __forceinline__ float sum8_dpp(float x) { x += DPPX(x, 0xB1); x += DPPX(x, 0x4E); x += DPPX(x, 0x141); return x; }
; __device__ __forceinline__ void prep2_phase(const Args& a, int e) {
;     ...
;             kk[i] = k[i] * kkw[i]; ss += kk[i] * kk[i];
;             km[i] = k[i] * (1.0f + (av[i] - 1.0f) * kaw[i]);
;         }
;         ss = sum8_dpp(ss);
;         const float rn = rsqrtf(ss + 1e-12f);
; #pragma unroll
;         for (int i = 0; i < 8; ++i) { kk[i] *= rn; ka[i] = kk[i] * av[i]; }
;         bf16* sa = SA + ((size_t)m * 8 + h) * 256 + (lane & 7) * 8; bf16* sb = SB + ((size_t)m * 8 + h) * 128 + (lane & 7) * 8;
;         *(v4u*)(sa) = pack8(r); *(v4u*)(sa + 64) = pack8(u); *(v4u*)(sa + 128) = pack8(km); *(v4u*)(sa + 192) = pack8(v);
;         *(v4u*)(sb) = pack8(kk); *(v4u*)(sb + 64) = pack8(ka);
;         bf16* pb = PB + (size_t)m * APROJ + 1536;
;         float xa[16]; unpack8(*(const v4u*)(pb), xa); unpack8(*(const v4u*)(pb + 8), xa + 8);
;         f32x4 acc = ab;
; #pragma unroll
;         for (int i = 0; i < 16; ++i) { const f32x4 wv = *(const f32x4*)(aup + i * 256 + 4 * lane); acc += xa[i] * wv; }
	v_mul_f32_e32 v118, 0xbfb8aa3b, v118
	v_exp_f32_e32 v118, v118
	s_nop 0
	v_add_f32_e32 v118, 1.0, v118
	v_rcp_f32_e32 v164, v118
	v_pk_mul_f32 v[118:119], v[60:61], v[102:103]
	v_add_f32_e32 v102, v128, v129
	v_add_f32_e32 v102, v130, v102
	v_add_f32_e32 v102, v131, v102
	v_add_f32_e32 v102, v156, v102
	v_pk_mul_f32 v[136:137], v[118:119], v[118:119]
	v_add_f32_e32 v102, v157, v102
	v_add_f32_e32 v102, v136, v102
	v_add_f32_e32 v102, v137, v102
	v_add_f32_e32 v128, -1.0, v164
	v_fma_f32 v128, v49, v128, 1.0
	v_add_f32_dpp v102, v102, v102 quad_perm:[1,0,3,2] row_mask:0xf bank_mask:0xf bound_ctrl:1
	v_mul_f32_e32 v128, v103, v128
	s_nop 0
	v_add_f32_dpp v102, v102, v102 quad_perm:[2,3,0,1] row_mask:0xf bank_mask:0xf bound_ctrl:1
	s_nop 1
	v_add_f32_dpp v102, v102, v102 row_half_mirror row_mask:0xf bank_mask:0xf bound_ctrl:1
	v_add_f32_e32 v102, 0x2b8cbccc, v102
	v_cmp_gt_f32_e32 vcc, s50, v102
	v_mul_f32_e32 v103, 0x4b800000, v102
	s_nop 0
	v_cndmask_b32_e32 v102, v102, v103, vcc
	v_rsq_f32_e32 v102, v102
	s_nop 0
	v_mul_f32_e32 v103, 0x45800000, v102
	v_cndmask_b32_e32 v102, v102, v103, vcc
	v_mul_f32_e32 v126, v126, v102
	v_mul_f32_e32 v127, v127, v102
	v_mul_f32_e32 v124, v124, v102
	v_mul_f32_e32 v125, v125, v102
	v_mul_f32_e32 v137, v149, v102
	v_mul_f32_e32 v129, v134, v126
	v_mul_f32_e32 v130, v135, v127
	v_mul_f32_e32 v131, v144, v124
	v_mul_f32_e32 v134, v147, v125
	v_mul_f32_e32 v135, v148, v102
	v_mul_f32_e32 v144, v146, v137
	v_mul_f32_e32 v146, v118, v102
	v_mul_f32_e32 v147, v119, v102
	v_cvt_pk_bf16_f32 v102, v106, v107
	v_cvt_pk_bf16_f32 v103, v104, v105
	v_cvt_pk_bf16_f32 v104, v110, v111
	v_cvt_pk_bf16_f32 v105, v108, v109
	global_store_dwordx4 v[94:95], v[102:105], off
	v_lshl_add_u64 v[118:119], s[22:23], 0, v[90:91]
	v_add_co_u32_e32 v106, vcc, s0, v118
	v_cvt_pk_bf16_f32 v102, v132, v133
	v_cvt_pk_bf16_f32 v103, v142, v143
	v_cvt_pk_bf16_f32 v104, v123, v145
	v_cvt_pk_bf16_f32 v105, v138, v163
	global_store_dwordx4 v[94:95], v[102:105], off offset:128
	s_nop 0
	v_addc_co_u32_e32 v107, vcc, 0, v119, vcc
	v_cvt_pk_bf16_f32 v102, v63, v140
	v_cvt_pk_bf16_f32 v103, v141, v122
	v_cvt_pk_bf16_f32 v104, v160, v161
	v_cvt_pk_bf16_f32 v105, v162, v128
	global_store_dwordx4 v[94:95], v[102:105], off offset:256
	v_mul_f32_e32 v136, v158, v135
	v_mul_f32_e32 v139, v139, v146
	v_cvt_pk_bf16_f32 v102, v112, v113
	v_cvt_pk_bf16_f32 v103, v114, v115
	v_cvt_pk_bf16_f32 v104, v116, v117
	v_cvt_pk_bf16_f32 v105, v120, v121
	global_store_dwordx4 v[94:95], v[102:105], off offset:384
	v_mul_f32_e32 v148, v164, v147
	v_lshl_add_u64 v[90:91], v[90:91], 0, s[18:19]
	v_cvt_pk_bf16_f32 v102, v126, v127
	v_cvt_pk_bf16_f32 v103, v124, v125
	v_cvt_pk_bf16_f32 v104, v135, v137
	v_cvt_pk_bf16_f32 v105, v146, v147
	global_store_dwordx4 v[106:107], v[102:105], off
	v_lshl_add_u64 v[94:95], v[94:95], 0, s[28:29]
	s_nop 0
	v_cvt_pk_bf16_f32 v102, v129, v130
	v_cvt_pk_bf16_f32 v103, v131, v134
	v_cvt_pk_bf16_f32 v104, v136, v144
	v_cvt_pk_bf16_f32 v105, v139, v148
	global_store_dwordx4 v[106:107], v[102:105], off offset:128
	s_nop 1
	v_lshl_add_u64 v[102:103], s[22:23], 0, v[92:93]
	v_lshl_add_u64 v[106:107], v[102:103], 0, s[68:69]
	v_add_co_u32_e32 v102, vcc, s42, v102
	s_nop 1
	v_addc_co_u32_e32 v103, vcc, 0, v103, vcc
	global_load_dwordx4 v[102:105], v[102:103], off offset:3072
	s_nop 0
	global_load_dwordx4 v[106:109], v[106:107], off offset:16
	s_waitcnt vmcnt(1)
	v_lshlrev_b32_e32 v118, 16, v104
	v_and_b32_e32 v120, 0xffff0000, v104
	v_lshlrev_b32_e32 v122, 16, v105
	v_and_b32_e32 v124, 0xffff0000, v105
	s_waitcnt vmcnt(0)
	v_lshlrev_b32_e32 v126, 16, v106
	v_and_b32_e32 v128, 0xffff0000, v106
	v_lshlrev_b32_e32 v130, 16, v107
	v_and_b32_e32 v132, 0xffff0000, v107
	s_nop 0
	v_lshlrev_b32_e32 v110, 16, v102
	v_and_b32_e32 v112, 0xffff0000, v102
	v_lshlrev_b32_e32 v114, 16, v103
	v_and_b32_e32 v116, 0xffff0000, v103
	v_lshlrev_b32_e32 v134, 16, v108
	v_and_b32_e32 v108, 0xffff0000, v108
	v_lshlrev_b32_e32 v136, 16, v109
	v_and_b32_e32 v102, 0xffff0000, v109
	v_pk_fma_f32 v[138:139], v[206:207], v[110:111], v[50:51] op_sel_hi:[1,0,1]
	v_pk_fma_f32 v[110:111], v[208:209], v[110:111], v[52:53] op_sel_hi:[1,0,1]
	s_nop 0
	v_pk_fma_f32 v[110:111], v[212:213], v[112:113], v[110:111] op_sel_hi:[1,0,1]
	v_pk_fma_f32 v[112:113], v[210:211], v[112:113], v[138:139] op_sel_hi:[1,0,1]
	s_nop 0
	v_pk_fma_f32 v[112:113], v[214:215], v[114:115], v[112:113] op_sel_hi:[1,0,1]
	v_pk_fma_f32 v[110:111], v[216:217], v[114:115], v[110:111] op_sel_hi:[1,0,1]
	s_nop 0
	v_pk_fma_f32 v[110:111], v[220:221], v[116:117], v[110:111] op_sel_hi:[1,0,1]
	v_pk_fma_f32 v[112:113], v[218:219], v[116:117], v[112:113] op_sel_hi:[1,0,1]
	s_nop 0
	v_pk_fma_f32 v[112:113], v[118:119], v[222:223], v[112:113] op_sel_hi:[0,1,1]
	v_pk_fma_f32 v[110:111], v[118:119], v[224:225], v[110:111] op_sel_hi:[0,1,1]
	s_nop 0
	v_pk_fma_f32 v[110:111], v[120:121], v[228:229], v[110:111] op_sel_hi:[0,1,1]
	v_pk_fma_f32 v[112:113], v[120:121], v[226:227], v[112:113] op_sel_hi:[0,1,1]
	s_nop 0
	v_pk_fma_f32 v[112:113], v[122:123], v[230:231], v[112:113] op_sel_hi:[0,1,1]
	v_pk_fma_f32 v[110:111], v[122:123], v[232:233], v[110:111] op_sel_hi:[0,1,1]
	s_nop 0
	v_pk_fma_f32 v[110:111], v[124:125], v[236:237], v[110:111] op_sel_hi:[0,1,1]
	v_pk_fma_f32 v[112:113], v[124:125], v[234:235], v[112:113] op_sel_hi:[0,1,1]
	s_nop 0
	v_pk_fma_f32 v[112:113], v[126:127], v[238:239], v[112:113] op_sel_hi:[0,1,1]
	v_pk_fma_f32 v[110:111], v[126:127], v[240:241], v[110:111] op_sel_hi:[0,1,1]
	s_nop 0
	v_pk_fma_f32 v[110:111], v[128:129], v[244:245], v[110:111] op_sel_hi:[0,1,1]
	v_pk_fma_f32 v[112:113], v[128:129], v[242:243], v[112:113] op_sel_hi:[0,1,1]
; __device__ __forceinline__ unsigned cvt_pk_bf16(float lo, float hi) { unsigned r; asm volatile("v_cvt_pk_bf16_f32 %0, %1, %2" : "=v"(r) : "v"(lo), "v"(hi)); return r; }
; __device__ __forceinline__ float softplus_f(float x) { return fmaxf(x, 0.f) + __logf(1.0f + __expf(-fabsf(x))); }
; __device__ __forceinline__ void prep2_phase(const Args& a, int e) {
;     ...
;         for (int i = 0; i < 16; ++i) { const f32x4 wv = *(const f32x4*)(aup + i * 256 + 4 * lane); acc += xa[i] * wv; }
;         float ug[4];
; #pragma unroll
;         for (int i = 0; i < 4; ++i) ug[i] = 1.0f - __expf(-softplus_f(-acc[i]) * (1.0f / 16.0f));
;         v2u o; o.x = cvt_pk_bf16(ug[0], ug[1]); o.y = cvt_pk_bf16(ug[2], ug[3]);
;         *(v2u*)(pb + 4 * lane) = o;
;     }
	s_nop 0
	v_pk_fma_f32 v[112:113], v[130:131], v[246:247], v[112:113] op_sel_hi:[0,1,1]
	v_pk_fma_f32 v[110:111], v[130:131], v[248:249], v[110:111] op_sel_hi:[0,1,1]
	s_nop 0
	v_pk_fma_f32 v[110:111], v[132:133], v[168:169], v[110:111] op_sel_hi:[0,1,1]
	v_pk_fma_f32 v[112:113], v[132:133], v[166:167], v[112:113] op_sel_hi:[0,1,1]
	s_nop 0
	v_pk_fma_f32 v[112:113], v[134:135], v[170:171], v[112:113] op_sel_hi:[0,1,1]
	v_pk_fma_f32 v[110:111], v[134:135], v[172:173], v[110:111] op_sel_hi:[0,1,1]
	s_nop 0
	v_pk_fma_f32 v[110:111], v[108:109], v[176:177], v[110:111] op_sel_hi:[0,1,1]
	v_pk_fma_f32 v[108:109], v[108:109], v[174:175], v[112:113] op_sel_hi:[0,1,1]
	s_nop 0
	v_pk_fma_f32 v[112:113], v[136:137], v[178:179], v[108:109] op_sel_hi:[0,1,1]
	v_pk_fma_f32 v[104:105], v[136:137], v[180:181], v[110:111] op_sel_hi:[0,1,1]
	s_nop 0
	v_pk_fma_f32 v[104:105], v[102:103], v[194:195], v[104:105] op_sel_hi:[0,1,1]
	v_pk_fma_f32 v[102:103], v[102:103], v[192:193], v[112:113] op_sel_hi:[0,1,1]
	v_max_f32_e64 v63, -v102, 0
	v_mul_f32_e64 v102, |v102|, s43
	v_exp_f32_e32 v102, v102
	s_nop 0
	v_add_f32_e32 v102, 1.0, v102
	v_cmp_gt_f32_e32 vcc, s50, v102
	s_nop 1
	v_cndmask_b32_e64 v106, 0, 32, vcc
	v_ldexp_f32 v102, v102, v106
	v_log_f32_e32 v102, v102
	s_nop 0
	v_mul_f32_e32 v106, 0x3f317217, v102
	v_fma_f32 v106, v102, s51, -v106
	v_fmac_f32_e32 v106, 0x3377d1cf, v102
	v_fmac_f32_e32 v106, 0x3f317217, v102
	v_cmp_lt_f32_e64 s[0:1], |v102|, s65
	s_nop 1
	v_cndmask_b32_e64 v102, v102, v106, s[0:1]
	v_cndmask_b32_e32 v106, 0, v199, vcc
	v_sub_f32_e32 v102, v102, v106
	v_add_f32_e32 v63, v63, v102
	v_max_f32_e64 v102, -v103, 0
	v_mul_f32_e64 v103, |v103|, s43
	v_exp_f32_e32 v103, v103
	v_mul_f32_e32 v63, 0xbd800000, v63
	v_mul_f32_e32 v63, 0x3fb8aa3b, v63
	v_exp_f32_e32 v63, v63
	v_add_f32_e32 v103, 1.0, v103
	v_cmp_gt_f32_e32 vcc, s50, v103
	v_sub_f32_e32 v63, 1.0, v63
	s_nop 0
	v_cndmask_b32_e64 v106, 0, 32, vcc
	v_ldexp_f32 v103, v103, v106
	v_log_f32_e32 v103, v103
	s_nop 0
	v_mul_f32_e32 v106, 0x3f317217, v103
	v_fma_f32 v106, v103, s51, -v106
	v_fmac_f32_e32 v106, 0x3377d1cf, v103
	v_fmac_f32_e32 v106, 0x3f317217, v103
	v_cmp_lt_f32_e64 s[0:1], |v103|, s65
	s_nop 1
	v_cndmask_b32_e64 v103, v103, v106, s[0:1]
	v_cndmask_b32_e32 v106, 0, v199, vcc
	v_sub_f32_e32 v103, v103, v106
	v_add_f32_e32 v102, v102, v103
	v_max_f32_e64 v103, -v104, 0
	v_mul_f32_e64 v104, |v104|, s43
	v_exp_f32_e32 v104, v104
	v_mul_f32_e32 v102, 0xbd800000, v102
	v_mul_f32_e32 v102, 0x3fb8aa3b, v102
	v_exp_f32_e32 v102, v102
	v_add_f32_e32 v104, 1.0, v104
	v_cmp_gt_f32_e32 vcc, s50, v104
	v_sub_f32_e32 v102, 1.0, v102
	s_nop 0
	v_cndmask_b32_e64 v106, 0, 32, vcc
	v_ldexp_f32 v104, v104, v106
	v_log_f32_e32 v104, v104
	v_cvt_pk_bf16_f32 v102, v63, v102
	s_nop 0
	v_mul_f32_e32 v106, 0x3f317217, v104
	v_fma_f32 v106, v104, s51, -v106
	v_fmac_f32_e32 v106, 0x3377d1cf, v104
	v_fmac_f32_e32 v106, 0x3f317217, v104
	v_cmp_lt_f32_e64 s[0:1], |v104|, s65
	s_nop 1
	v_cndmask_b32_e64 v104, v104, v106, s[0:1]
	v_cndmask_b32_e32 v106, 0, v199, vcc
	v_sub_f32_e32 v104, v104, v106
	v_add_f32_e32 v103, v103, v104
	v_max_f32_e64 v104, -v105, 0
	v_mul_f32_e64 v105, |v105|, s43
	v_exp_f32_e32 v105, v105
	v_mul_f32_e32 v103, 0xbd800000, v103
	v_mul_f32_e32 v103, 0x3fb8aa3b, v103
	v_exp_f32_e32 v103, v103
	v_add_f32_e32 v105, 1.0, v105
	v_cmp_gt_f32_e32 vcc, s50, v105
	v_sub_f32_e32 v103, 1.0, v103
	s_nop 0
	v_cndmask_b32_e64 v106, 0, 32, vcc
	v_ldexp_f32 v105, v105, v106
	v_log_f32_e32 v105, v105
	s_nop 0
	v_mul_f32_e32 v106, 0x3f317217, v105
	v_fma_f32 v106, v105, s51, -v106
	v_fmac_f32_e32 v106, 0x3377d1cf, v105
	v_fmac_f32_e32 v106, 0x3f317217, v105
	v_cmp_lt_f32_e64 s[0:1], |v105|, s65
	s_nop 1
	v_cndmask_b32_e64 v105, v105, v106, s[0:1]
	v_cndmask_b32_e32 v106, 0, v199, vcc
	v_sub_f32_e32 v105, v105, v106
	v_add_f32_e32 v104, v104, v105
	v_mul_f32_e32 v104, 0xbd800000, v104
	v_mul_f32_e32 v104, 0x3fb8aa3b, v104
	v_exp_f32_e32 v104, v104
	v_readlane_b32 s0, v253, 26
	v_readlane_b32 s1, v253, 27
	v_cmp_lt_i32_e32 vcc, s53, v62
	v_sub_f32_e32 v104, 1.0, v104
	v_cvt_pk_bf16_f32 v103, v103, v104
	v_lshl_add_u64 v[104:105], s[22:23], 0, v[100:101]
	v_lshl_add_u64 v[92:93], v[92:93], 0, s[0:1]
	v_lshl_add_u64 v[98:99], v[98:99], 0, s[0:1]
	v_lshl_add_u64 v[100:101], v[100:101], 0, s[0:1]
	s_or_b64 s[30:31], vcc, s[30:31]
	global_store_dwordx2 v[104:105], v[102:103], off
	s_andn2_b64 exec, exec, s[30:31]
	s_cbranch_execz .LBB0_274
; __device__ __forceinline__ void prep2_phase(const Args& a, int e) {
;     ...
;     for (int m = gw; m < MT; m += ngw) {
;         const bf16* pr = PA + (size_t)m * APROJ;
;         float r[8], k[8], v[8], pq[8];
;         unpack8(*(const v4u*)(pr + c8), r); unpack8(*(const v4u*)(pr + 512 + c8), k); unpack8(*(const v4u*)(pr + 1024 + c8), v);
;         const int t = m < MP ? (m & (TPR - 1)) : ((m - MP) & (TSM - 1));
;         if (t > 0) {
;             unpack8(*(const v4u*)(pr - APROJ + c8), pq);
; #pragma unroll
;             for (int i = 0; i < 8; ++i) r[i] += (pq[i] - r[i]) * mur[i];
;             unpack8(*(const v4u*)(pr - APROJ + 512 + c8), pq);
; #pragma unroll
;             for (int i = 0; i < 8; ++i) k[i] += (pq[i] - k[i]) * muk[i];
;             unpack8(*(const v4u*)(pr - APROJ + 1024 + c8), pq);
; #pragma unroll
;             for (int i = 0; i < 8; ++i) v[i] += (pq[i] - v[i]) * muv[i];
.LBB0_266:
	v_lshl_add_u64 v[156:157], s[22:23], 0, v[98:99]
	v_add_co_u32_e32 v110, vcc, 0x22c80000, v156
	v_cmp_lt_i32_e64 s[38:39], s59, v62
	s_nop 0
	v_addc_co_u32_e32 v111, vcc, 0, v157, vcc
	global_load_dwordx4 v[102:105], v[110:111], off
	global_load_dwordx4 v[106:109], v[110:111], off offset:1024
	s_nop 0
	global_load_dwordx4 v[110:113], v[110:111], off offset:2048
	v_lshl_add_u64 v[72:73], s[22:23], 0, v[96:97]
	s_mov_b32 s0, 0xe780000
	v_add_co_u32_e32 v74, vcc, s0, v72
	s_mov_b32 s0, 0x12880000
	s_nop 0
	v_addc_co_u32_e32 v75, vcc, 0, v73, vcc
	v_add_co_u32_e32 v76, vcc, s0, v72
	global_load_dwordx4 v[64:67], v[74:75], off
	s_nop 0
	v_addc_co_u32_e32 v77, vcc, 0, v73, vcc
	global_load_dwordx4 v[68:71], v[76:77], off
	v_cmp_gt_i32_e32 vcc, s52, v62
	s_waitcnt vmcnt(4)
	v_lshlrev_b32_e32 v140, 16, v102
	v_cndmask_b32_e32 v63, 63, v198, vcc
	v_and_b32_e32 v63, v63, v62
	v_and_b32_e32 v141, 0xffff0000, v102
	v_lshlrev_b32_e32 v138, 16, v103
	v_and_b32_e32 v139, 0xffff0000, v103
	v_lshlrev_b32_e32 v134, 16, v104
	v_and_b32_e32 v135, 0xffff0000, v104
	v_lshlrev_b32_e32 v136, 16, v105
	v_and_b32_e32 v137, 0xffff0000, v105
	s_waitcnt vmcnt(3)
	v_lshlrev_b32_e32 v148, 16, v106
	v_and_b32_e32 v149, 0xffff0000, v106
	v_lshlrev_b32_e32 v146, 16, v107
	v_and_b32_e32 v147, 0xffff0000, v107
	v_lshlrev_b32_e32 v144, 16, v108
	v_and_b32_e32 v145, 0xffff0000, v108
	v_lshlrev_b32_e32 v142, 16, v109
	v_and_b32_e32 v143, 0xffff0000, v109
	s_waitcnt vmcnt(2)
	v_lshlrev_b32_e32 v132, 16, v110
	v_and_b32_e32 v133, 0xffff0000, v110
	v_lshlrev_b32_e32 v130, 16, v111
	v_and_b32_e32 v131, 0xffff0000, v111
	v_lshlrev_b32_e32 v128, 16, v112
	v_and_b32_e32 v129, 0xffff0000, v112
	v_lshlrev_b32_e32 v126, 16, v113
	v_and_b32_e32 v127, 0xffff0000, v113
	v_cmp_ne_u32_e32 vcc, 0, v63
	s_and_saveexec_b64 s[0:1], vcc
	s_xor_b64 s[0:1], exec, s[0:1]
	s_cbranch_execz .LBB0_268
	v_add_co_u32_e32 v116, vcc, 0x22c7f000, v156
	s_nop 1
	v_addc_co_u32_e32 v117, vcc, 0, v157, vcc
	global_load_dwordx4 v[110:113], v[116:117], off offset:512
	s_waitcnt vmcnt(0)
	v_lshlrev_b32_e32 v102, 16, v110
	v_and_b32_e32 v103, 0xffff0000, v110
	v_pk_add_f32 v[102:103], v[102:103], v[140:141] neg_lo:[0,1] neg_hi:[0,1]
	s_nop 0
	v_pk_fma_f32 v[106:107], v[6:7], v[102:103], v[140:141]
	v_lshlrev_b32_e32 v102, 16, v111
	v_and_b32_e32 v103, 0xffff0000, v111
	v_pk_add_f32 v[102:103], v[102:103], v[138:139] neg_lo:[0,1] neg_hi:[0,1]
	s_nop 0
	v_pk_fma_f32 v[104:105], v[8:9], v[102:103], v[138:139]
	v_lshlrev_b32_e32 v102, 16, v112
	v_and_b32_e32 v103, 0xffff0000, v112
	v_pk_add_f32 v[102:103], v[102:103], v[134:135] neg_lo:[0,1] neg_hi:[0,1]
	s_nop 0
	v_pk_fma_f32 v[110:111], v[2:3], v[102:103], v[134:135]
	v_lshlrev_b32_e32 v102, 16, v113
	v_and_b32_e32 v103, 0xffff0000, v113
	global_load_dwordx4 v[112:115], v[116:117], off offset:1536
	v_pk_add_f32 v[102:103], v[102:103], v[136:137] neg_lo:[0,1] neg_hi:[0,1]
	s_nop 0
	v_pk_fma_f32 v[108:109], v[4:5], v[102:103], v[136:137]
	global_load_dwordx4 v[134:137], v[116:117], off offset:2560
	s_waitcnt vmcnt(1)
	v_lshlrev_b32_e32 v102, 16, v112
	v_and_b32_e32 v103, 0xffff0000, v112
	v_pk_add_f32 v[102:103], v[102:103], v[148:149] neg_lo:[0,1] neg_hi:[0,1]
	s_waitcnt vmcnt(0)
	v_lshlrev_b32_e32 v112, 16, v134
	v_pk_fma_f32 v[124:125], v[14:15], v[102:103], v[148:149]
	v_lshlrev_b32_e32 v102, 16, v113
	v_and_b32_e32 v103, 0xffff0000, v113
	v_pk_add_f32 v[102:103], v[102:103], v[146:147] neg_lo:[0,1] neg_hi:[0,1]
	v_and_b32_e32 v113, 0xffff0000, v134
	v_pk_fma_f32 v[122:123], v[16:17], v[102:103], v[146:147]
	v_lshlrev_b32_e32 v102, 16, v114
	v_and_b32_e32 v103, 0xffff0000, v114
	v_pk_add_f32 v[102:103], v[102:103], v[144:145] neg_lo:[0,1] neg_hi:[0,1]
	v_lshlrev_b32_e32 v114, 16, v135
	v_pk_fma_f32 v[118:119], v[10:11], v[102:103], v[144:145]
	v_lshlrev_b32_e32 v102, 16, v115
	v_and_b32_e32 v103, 0xffff0000, v115
	v_and_b32_e32 v115, 0xffff0000, v135
	v_lshlrev_b32_e32 v116, 16, v136
	v_and_b32_e32 v117, 0xffff0000, v136
	v_lshlrev_b32_e32 v120, 16, v137
	v_and_b32_e32 v121, 0xffff0000, v137
	v_pk_add_f32 v[102:103], v[102:103], v[142:143] neg_lo:[0,1] neg_hi:[0,1]
	v_pk_add_f32 v[112:113], v[112:113], v[132:133] neg_lo:[0,1] neg_hi:[0,1]
	v_pk_add_f32 v[114:115], v[114:115], v[130:131] neg_lo:[0,1] neg_hi:[0,1]
	v_pk_add_f32 v[116:117], v[116:117], v[128:129] neg_lo:[0,1] neg_hi:[0,1]
	v_pk_add_f32 v[120:121], v[120:121], v[126:127] neg_lo:[0,1] neg_hi:[0,1]
	v_pk_fma_f32 v[102:103], v[12:13], v[102:103], v[142:143]
	v_pk_fma_f32 v[112:113], v[18:19], v[112:113], v[132:133]
	v_pk_fma_f32 v[114:115], v[20:21], v[114:115], v[130:131]
	v_pk_fma_f32 v[116:117], v[22:23], v[116:117], v[128:129]
	v_pk_fma_f32 v[120:121], v[24:25], v[120:121], v[126:127]

; __device__ __forceinline__ float bf_lo(unsigned w) { return __uint_as_float(w << 16); }
; __device__ __forceinline__ float bf_hi(unsigned w) { return __uint_as_float(w & 0xffff0000u); }
; __device__ __forceinline__ float sigmoid_f(float x) { return __builtin_amdgcn_rcpf(1.0f + __expf(-x)); }
; __device__ __forceinline__ void prep1_phase(const Args& a, int e) {
;     ...
;     for (int m = gw; m < MT; m += ngw) {
;         const v2u pw = *(const v2u*)(PA + (size_t)m * APROJ + c);
;         float p[4] = {bf_lo(pw.x), bf_hi(pw.x), bf_lo(pw.y), bf_hi(pw.y)}, q[4];
;         const int t = m < MP ? (m & (TPR - 1)) : ((m - MP) & (TSM - 1));
;         if (t > 0) { const v2u qw = *(const v2u*)(PA + (size_t)(m - 1) * APROJ + c); q[0] = bf_lo(qw.x); q[1] = bf_hi(qw.x); q[2] = bf_lo(qw.y); q[3] = bf_hi(qw.y); }
;         else if (m < MP) { q[0] = q[1] = q[2] = q[3] = 0.f; }
;         else { const f32x4 s = *(const f32x4*)(shift0 + (size_t)((m - MP) >> 6) * APROJ + c); q[0] = s.x; q[1] = s.y; q[2] = s.z; q[3] = s.w; }
;         float r[4];
; #pragma unroll
;         for (int i = 0; i < 4; ++i) { const float xs = p[i] + (q[i] - p[i]) * mu4[i]; r[i] = lane < 16 ? 2.0f * sigmoid_f(2.0f * xs) - 1.0f : (lane < 32 ? xs : sigmoid_f(xs))    ; }
.LBB0_345:
	s_or_b64 exec, exec, s[28:29]
	v_readlane_b32 s30, v253, 26
	v_readlane_b32 s31, v253, 27
	s_mov_b32 m0, 0x20100
	v_add_u32_e32 v22, s64, v10
	s_movk_i32 s3, 0xe00
	v_lshl_add_u64 v[24:25], v[18:19], 0, s[30:31]
	v_add_u32_e32 v22, -1, v22
	global_load_lds_dword v[24:25], off
	v_mad_i64_i32 v[26:27], s[30:31], v22, s3, v[14:15]
	global_load_lds_dword v[26:27], off
	s_waitcnt vmcnt(2)
	v_lshlrev_b32_e32 v11, 16, v20
	v_sub_f32_e32 v0, v6, v11
	v_fmac_f32_e32 v11, v2, v0
	s_and_saveexec_b64 s[0:1], vcc
	s_xor_b64 s[0:1], exec, s[0:1]
	s_cbranch_execz .LBB0_347
	v_mul_f32_e32 v0, 0xbfb8aa3b, v11
	v_exp_f32_e32 v0, v0
	s_nop 0
	v_add_f32_e32 v0, 1.0, v0
	v_rcp_f32_e32 v0, v0
	s_nop 0
	v_cndmask_b32_e64 v0, v0, v11, s[38:39]

; __device__ __forceinline__ void transpose_item(const float* W, int ldw, int mode, bf16* WT, int K, int N, int it, int lane) {
;     const int nblk = N / 64;
;     const int kb = it / nblk, nb = it - kb * nblk, k0 = 64 * kb, n = 64 * nb + lane;
;     const int sc = src_col(mode, n); const float msk = sc >= 0 ? 1.f : 0.f; const int scc = sc >= 0 ? sc : 0;
;     const float* wp = W + (size_t)k0 * ldw + scc; bf16* op = WT + (size_t)n * K + k0;
; #pragma unroll 4
;     for (int k8 = 0; k8 < 8; ++k8) {
;         float f[8];
; #pragma unroll
;         for (int i = 0; i < 8; ++i) f[i] = wp[(size_t)(8 * k8 + i) * ldw] * msk;
;         *(v4u*)(op + 8 * k8) = pack8(f);
;     }
.LBB0_543:
	global_load_dword v32, v[2:3], off
	v_lshl_add_u64 v[28:29], v[2:3], 0, v[8:9]
	global_load_dword v33, v[28:29], off
	v_lshl_add_u64 v[28:29], v[28:29], 0, v[8:9]
	global_load_dword v34, v[28:29], off
	v_lshl_add_u64 v[28:29], v[28:29], 0, v[8:9]
	global_load_dword v35, v[28:29], off
	v_lshl_add_u64 v[28:29], v[28:29], 0, v[8:9]
	global_load_dword v36, v[28:29], off
	v_lshl_add_u64 v[28:29], v[28:29], 0, v[8:9]
	global_load_dword v37, v[28:29], off
	v_lshl_add_u64 v[28:29], v[28:29], 0, v[8:9]
	global_load_dword v38, v[28:29], off
	v_lshl_add_u64 v[28:29], v[28:29], 0, v[8:9]
	global_load_dword v39, v[28:29], off
	v_lshl_add_u64 v[28:29], v[28:29], 0, v[8:9]
	global_load_dword v40, v[28:29], off
	v_lshl_add_u64 v[28:29], v[28:29], 0, v[8:9]
	global_load_dword v41, v[28:29], off
	v_lshl_add_u64 v[28:29], v[28:29], 0, v[8:9]
	global_load_dword v42, v[28:29], off
	v_lshl_add_u64 v[28:29], v[28:29], 0, v[8:9]
	global_load_dword v43, v[28:29], off
	v_lshl_add_u64 v[28:29], v[28:29], 0, v[8:9]
	global_load_dword v44, v[28:29], off
	v_lshl_add_u64 v[28:29], v[28:29], 0, v[8:9]
	global_load_dword v45, v[28:29], off
	v_lshl_add_u64 v[28:29], v[28:29], 0, v[8:9]
	global_load_dword v46, v[28:29], off
	v_lshl_add_u64 v[28:29], v[28:29], 0, v[8:9]
	global_load_dword v47, v[28:29], off
	v_lshl_add_u64 v[28:29], v[28:29], 0, v[8:9]
	global_load_dword v48, v[28:29], off
	v_lshl_add_u64 v[28:29], v[28:29], 0, v[8:9]
	global_load_dword v49, v[28:29], off
	v_lshl_add_u64 v[28:29], v[28:29], 0, v[8:9]
	global_load_dword v50, v[28:29], off
	v_lshl_add_u64 v[28:29], v[28:29], 0, v[8:9]
	global_load_dword v51, v[28:29], off
	v_lshl_add_u64 v[28:29], v[28:29], 0, v[8:9]
	global_load_dword v52, v[28:29], off
	v_lshl_add_u64 v[28:29], v[28:29], 0, v[8:9]
	global_load_dword v53, v[28:29], off
	v_lshl_add_u64 v[28:29], v[28:29], 0, v[8:9]
	global_load_dword v54, v[28:29], off
	v_lshl_add_u64 v[28:29], v[28:29], 0, v[8:9]
	global_load_dword v55, v[28:29], off
	v_lshl_add_u64 v[28:29], v[28:29], 0, v[8:9]
	global_load_dword v56, v[28:29], off
	v_lshl_add_u64 v[28:29], v[28:29], 0, v[8:9]
	global_load_dword v57, v[28:29], off
	v_lshl_add_u64 v[28:29], v[28:29], 0, v[8:9]
	global_load_dword v58, v[28:29], off
	v_lshl_add_u64 v[28:29], v[28:29], 0, v[8:9]
	global_load_dword v59, v[28:29], off
	v_lshl_add_u64 v[28:29], v[28:29], 0, v[8:9]
	global_load_dword v60, v[28:29], off
	v_lshl_add_u64 v[28:29], v[28:29], 0, v[8:9]
	global_load_dword v61, v[28:29], off
	v_lshl_add_u64 v[28:29], v[28:29], 0, v[8:9]
	global_load_dword v62, v[28:29], off
	v_lshl_add_u64 v[28:29], v[28:29], 0, v[8:9]
	global_load_dword v63, v[28:29], off
	v_lshl_add_u64 v[2:3], v[2:3], 0, v[6:7]
	v_lshl_add_u64 v[10:11], v[4:5], 0, s[6:7]
	s_add_u32 s6, s6, 64
	s_addc_u32 s7, s7, 0
	s_cmpk_lg_i32 s6, 0x80
	s_waitcnt vmcnt(24)
	v_mul_f32_e32 v32, v15, v32
	v_mul_f32_e32 v33, v15, v33
	v_mul_f32_e32 v34, v15, v34
	v_mul_f32_e32 v35, v15, v35
	v_mul_f32_e32 v36, v15, v36
	v_mul_f32_e32 v37, v15, v37
	v_mul_f32_e32 v38, v15, v38
	v_mul_f32_e32 v39, v15, v39
	v_cvt_pk_bf16_f32 v64, v32, v33
	v_cvt_pk_bf16_f32 v65, v34, v35
	v_cvt_pk_bf16_f32 v66, v36, v37
	v_cvt_pk_bf16_f32 v67, v38, v39
	global_store_dwordx4 v[10:11], v[64:67], off
	s_waitcnt vmcnt(17)
	v_mul_f32_e32 v40, v15, v40
	v_mul_f32_e32 v41, v15, v41
	v_mul_f32_e32 v42, v15, v42
	v_mul_f32_e32 v43, v15, v43
	v_mul_f32_e32 v44, v15, v44
	v_mul_f32_e32 v45, v15, v45
	v_mul_f32_e32 v46, v15, v46
	v_mul_f32_e32 v47, v15, v47
	v_cvt_pk_bf16_f32 v68, v40, v41
	v_cvt_pk_bf16_f32 v69, v42, v43
	v_cvt_pk_bf16_f32 v70, v44, v45
	v_cvt_pk_bf16_f32 v71, v46, v47
	global_store_dwordx4 v[10:11], v[68:71], off offset:16
	s_waitcnt vmcnt(10)
	v_mul_f32_e32 v48, v15, v48
	v_mul_f32_e32 v49, v15, v49
	v_mul_f32_e32 v50, v15, v50
	v_mul_f32_e32 v51, v15, v51
	v_mul_f32_e32 v52, v15, v52
	v_mul_f32_e32 v53, v15, v53
	v_mul_f32_e32 v54, v15, v54
	v_mul_f32_e32 v55, v15, v55
	v_cvt_pk_bf16_f32 v72, v48, v49
	v_cvt_pk_bf16_f32 v73, v50, v51
	v_cvt_pk_bf16_f32 v74, v52, v53
	v_cvt_pk_bf16_f32 v75, v54, v55
	global_store_dwordx4 v[10:11], v[72:75], off offset:32
	s_waitcnt vmcnt(3)
	v_mul_f32_e32 v56, v15, v56
	v_mul_f32_e32 v57, v15, v57
	v_mul_f32_e32 v58, v15, v58
	v_mul_f32_e32 v59, v15, v59
	v_mul_f32_e32 v60, v15, v60
	v_mul_f32_e32 v61, v15, v61
	v_mul_f32_e32 v62, v15, v62
	v_mul_f32_e32 v63, v15, v63
	v_cvt_pk_bf16_f32 v76, v56, v57
	v_cvt_pk_bf16_f32 v77, v58, v59
	v_cvt_pk_bf16_f32 v78, v60, v61
	v_cvt_pk_bf16_f32 v79, v62, v63
	global_store_dwordx4 v[10:11], v[76:79], off offset:48
	s_cbranch_scc1 .LBB0_543
	v_add_u32_e32 v13, s64, v13
	s_movk_i32 s3, 0x31ff
	v_cmp_lt_i32_e32 vcc, s3, v13
	s_or_b64 s[4:5], vcc, s[4:5]
	s_andn2_b64 exec, exec, s[4:5]
	s_cbranch_execnz .LBB0_474
